# P3 chunk deltas: the four V^T fragment loads of a unit requested together (were one per ks step behind vmcnt(0))
# speedup vs baseline: 1.0058x; 1.0009x over previous
; #define LAS __attribute__((address_space(3)))
; __device__ __forceinline__ unsigned pk2(float lo, float hi) { return f2bf(lo) | (f2bf(hi) << 16); }
; __device__ __forceinline__ float bf_lo(unsigned w) { return __uint_as_float(w << 16); }
; __device__ __forceinline__ float bf_hi(unsigned w) { return __uint_as_float(w & 0xffff0000u); }
; __device__ __forceinline__ f32x4 mfma16(bf16x8 a, bf16x8 b, f32x4 c) { return __builtin_amdgcn_mfma_f32_16x16x32_bf16(a, b, c, 0, 0, 0); }
; template <int MASK> __device__ __forceinline__ void phase3(const Args& a, LAS unsigned char* lds, int tid, int wave, int lane, int vcu, int G) {
;     ...
;             const bf16* vt = PT + (size_t)(R_MVT + hd * 128 + 16 * wave + i16) * MT + 128 * c + 8 * g;
;             const int q4 = i16 >> 2, p4 = i16 & 3;
; #pragma unroll
;             for (int ks = 0; ks < 4; ++ks) {
;                 const u32x4 aw = __builtin_bit_cast(u32x4, ldfrag(vt + 32 * ks));
;                 const f32x4 w0 = *(const LAS f32x4*)(wl + 32 * ks + 8 * g), w1 = *(const LAS f32x4*)(wl + 32 * ks + 8 * g + 4);
;                 u32x4 as, a1;
;                 as.x = pk2(bf_lo(aw.x) * w0[0], bf_hi(aw.x) * w0[1]); as.y = pk2(bf_lo(aw.y) * w0[2], bf_hi(aw.y) * w0[3]);
;                 as.z = pk2(bf_lo(aw.z) * w1[0], bf_hi(aw.z) * w1[1]); as.w = pk2(bf_lo(aw.w) * w1[2], bf_hi(aw.w) * w1[3]);
;                 a1.x = pk2(w0[0], w0[1]); a1.y = pk2(w0[2], w0[3]); a1.z = pk2(w1[0], w1[1]); a1.w = pk2(w1[2], w1[3]);
;                 const bf16x8 af = __builtin_bit_cast(bf16x8, as), af1 = __builtin_bit_cast(bf16x8, a1);
; #pragma unroll
;                 for (int n = 0; n < 8; ++n) {
;                     typedef short v4i16_t __attribute__((ext_vector_type(4)));
;                     const v4i16_t lo = __builtin_amdgcn_ds_read_tr16_b64_v4i16((LAS v4i16_t*)(LK + (32 * ks + 8 * g + q4) * 272 + 32 * n + 8 * p4));
;                     const v4i16_t hi = __builtin_amdgcn_ds_read_tr16_b64_v4i16((LAS v4i16_t*)(LK + (32 * ks + 8 * g + 4 + q4) * 272 + 32 * n + 8 * p4));
;                     const bf16x8 bfr = {lo[0], lo[1], lo[2], lo[3], hi[0], hi[1], hi[2], hi[3]};
;                     acc[n] = mfma16(af, bfr, acc[n]); if (wave == 0) accn[n] = mfma16(af1, bfr, accn[n]); }
.LBB0_633:
	v_lshl_add_u32 v1, s49, 7, v211
	v_mov_b64_e32 v[2:3], s[58:59]
	s_mov_b32 s2, 0x8800
	v_mad_u64_u32 v[2:3], s[2:3], v1, s2, v[2:3]
	s_ashr_i32 s49, s48, 31
	v_lshl_add_u64 v[2:3], s[48:49], 1, v[2:3]
	v_mov_b32_e32 v145, v95
	v_lshl_add_u64 v[82:83], v[2:3], 0, v[144:145]
	s_waitcnt lgkmcnt(0)
	s_barrier
	global_load_dwordx4 v[2:5], v[82:83], off
	global_load_dwordx4 v[170:173], v[82:83], off offset:64
	global_load_dwordx4 v[174:177], v[82:83], off offset:128
	global_load_dwordx4 v[178:181], v[82:83], off offset:192
	ds_read_b128 v[6:9], v212
	ds_read_b128 v[10:13], v212 offset:16
	s_mov_b32 s52, s53
	s_mov_b32 s54, s53
	s_mov_b32 s55, s53
	s_waitcnt lgkmcnt(1)
	v_mov_b32_e32 v16, v6
	v_mov_b32_e32 v17, v8
	s_waitcnt lgkmcnt(0)
	v_mov_b32_e32 v18, v10
	v_mov_b32_e32 v19, v12
	s_andn2_b64 vcc, exec, s[82:83]
	s_waitcnt vmcnt(3)
	v_lshlrev_b32_e32 v15, 16, v3
	v_lshlrev_b32_e32 v14, 16, v2
	v_pk_mul_f32 v[14:15], v[16:17], v[14:15]
	v_and_b32_e32 v3, 0xffff0000, v3
	v_and_b32_e32 v2, 0xffff0000, v2
	v_mov_b32_e32 v16, v7
	v_mov_b32_e32 v17, v9
	v_pk_mul_f32 v[2:3], v[16:17], v[2:3]
	v_lshlrev_b32_e32 v17, 16, v5
	v_lshlrev_b32_e32 v16, 16, v4
	v_pk_mul_f32 v[16:17], v[18:19], v[16:17]
	v_and_b32_e32 v5, 0xffff0000, v5
	v_and_b32_e32 v4, 0xffff0000, v4
	v_mov_b32_e32 v18, v11
	v_mov_b32_e32 v19, v13
	v_pk_mul_f32 v[4:5], v[18:19], v[4:5]
	v_bfe_u32 v19, v3, 16, 1
	v_bfe_u32 v1, v5, 16, 1
	v_bfe_u32 v18, v4, 16, 1
	v_add3_u32 v3, v3, v19, s81
	v_add3_u32 v4, v4, v18, s81
	v_add3_u32 v1, v5, v1, s81
	v_bfe_u32 v5, v14, 16, 1
	v_bfe_u32 v18, v15, 16, 1
	v_bfe_u32 v19, v16, 16, 1
	v_bfe_u32 v20, v2, 16, 1
	v_add3_u32 v16, v16, v19, s81
	v_add3_u32 v15, v15, v18, s81
	v_add3_u32 v5, v14, v5, s81
	v_add3_u32 v2, v2, v20, s81
	v_bfe_u32 v20, v17, 16, 1
	v_lshrrev_b32_e32 v5, 16, v5
	v_lshrrev_b32_e32 v14, 16, v15
	v_lshrrev_b32_e32 v15, 16, v16
	v_add3_u32 v17, v17, v20, s81
	v_and_or_b32 v36, v4, s80, v15
	v_and_or_b32 v35, v3, s80, v14
	v_and_or_b32 v34, v2, s80, v5
	v_bfe_u32 v2, v11, 16, 1
	v_bfe_u32 v3, v9, 16, 1
	v_bfe_u32 v4, v7, 16, 1
	v_lshrrev_b32_e32 v16, 16, v17
	v_add3_u32 v4, v7, v4, s81
	v_add3_u32 v3, v9, v3, s81
	v_add3_u32 v2, v11, v2, s81
	v_bfe_u32 v7, v8, 16, 1
	v_bfe_u32 v9, v10, 16, 1
	v_bfe_u32 v11, v12, 16, 1
	v_and_or_b32 v37, v1, s80, v16
	v_bfe_u32 v1, v13, 16, 1
	v_bfe_u32 v5, v6, 16, 1
	v_add3_u32 v11, v12, v11, s81
	v_add3_u32 v9, v10, v9, s81
	v_add3_u32 v7, v8, v7, s81
	v_add3_u32 v1, v13, v1, s81
	v_add3_u32 v5, v6, v5, s81
	v_lshrrev_b32_e32 v6, 16, v7
	v_lshrrev_b32_e32 v7, 16, v9
	v_lshrrev_b32_e32 v8, 16, v11
	v_and_or_b32 v41, v1, s80, v8
	v_and_or_b32 v40, v2, s80, v7
	v_and_or_b32 v39, v3, s80, v6
	ds_read_b64_tr_b16 v[6:7], v220 offset:1024
	ds_read_b64_tr_b16 v[8:9], v220 offset:2112
	s_waitcnt lgkmcnt(0)
	v_mfma_f32_16x16x32_bf16 v[70:73], v[34:37], v[6:9], 0
	v_lshrrev_b32_e32 v5, 16, v5
	v_and_or_b32 v38, v4, s80, v5
	v_mov_b64_e32 v[2:3], s[52:53]
	v_cndmask_b32_e64 v1, 0, 1, s[82:83]
	v_mov_b64_e32 v[4:5], s[54:55]
	v_cmp_ne_u32_e64 s[48:49], 1, v1
	s_cbranch_vccnz .LBB0_635
	v_mfma_f32_16x16x32_bf16 v[2:5], v[38:41], v[6:9], 0

; #define LAS __attribute__((address_space(3)))
; __device__ __forceinline__ unsigned pk2(float lo, float hi) { return f2bf(lo) | (f2bf(hi) << 16); }
; __device__ __forceinline__ float bf_lo(unsigned w) { return __uint_as_float(w << 16); }
; __device__ __forceinline__ float bf_hi(unsigned w) { return __uint_as_float(w & 0xffff0000u); }
; __device__ __forceinline__ f32x4 mfma16(bf16x8 a, bf16x8 b, f32x4 c) { return __builtin_amdgcn_mfma_f32_16x16x32_bf16(a, b, c, 0, 0, 0); }
; template <int MASK> __device__ __forceinline__ void phase3(const Args& a, LAS unsigned char* lds, int tid, int wave, int lane, int vcu, int G) {
;     ...
;             for (int ks = 0; ks < 4; ++ks) {
;                 const u32x4 aw = __builtin_bit_cast(u32x4, ldfrag(vt + 32 * ks));
;                 const f32x4 w0 = *(const LAS f32x4*)(wl + 32 * ks + 8 * g), w1 = *(const LAS f32x4*)(wl + 32 * ks + 8 * g + 4);
;                 u32x4 as, a1;
;                 as.x = pk2(bf_lo(aw.x) * w0[0], bf_hi(aw.x) * w0[1]); as.y = pk2(bf_lo(aw.y) * w0[2], bf_hi(aw.y) * w0[3]);
;                 as.z = pk2(bf_lo(aw.z) * w1[0], bf_hi(aw.z) * w1[1]); as.w = pk2(bf_lo(aw.w) * w1[2], bf_hi(aw.w) * w1[3]);
;                 a1.x = pk2(w0[0], w0[1]); a1.y = pk2(w0[2], w0[3]); a1.z = pk2(w1[0], w1[1]); a1.w = pk2(w1[2], w1[3]);
;                 const bf16x8 af = __builtin_bit_cast(bf16x8, as), af1 = __builtin_bit_cast(bf16x8, a1);
; #pragma unroll
;                 for (int n = 0; n < 8; ++n) {
;                     typedef short v4i16_t __attribute__((ext_vector_type(4)));
;                     const v4i16_t lo = __builtin_amdgcn_ds_read_tr16_b64_v4i16((LAS v4i16_t*)(LK + (32 * ks + 8 * g + q4) * 272 + 32 * n + 8 * p4));
;                     const v4i16_t hi = __builtin_amdgcn_ds_read_tr16_b64_v4i16((LAS v4i16_t*)(LK + (32 * ks + 8 * g + 4 + q4) * 272 + 32 * n + 8 * p4));
;                     const bf16x8 bfr = {lo[0], lo[1], lo[2], lo[3], hi[0], hi[1], hi[2], hi[3]};
;                     acc[n] = mfma16(af, bfr, acc[n]); if (wave == 0) accn[n] = mfma16(af1, bfr, accn[n]); }
.LBB0_649:
	s_nop 0
	ds_read_b128 v[38:41], v212 offset:128
	ds_read_b128 v[78:81], v212 offset:144
	s_and_b64 vcc, exec, s[48:49]
	s_waitcnt lgkmcnt(1)
	v_mov_b32_e32 v76, v38
	v_mov_b32_e32 v77, v40
	s_waitcnt lgkmcnt(0)
	v_mov_b32_e32 v84, v78
	v_mov_b32_e32 v85, v80
	s_waitcnt vmcnt(2)
	v_mov_b64_e32 v[34:35], v[170:171]
	v_mov_b64_e32 v[36:37], v[172:173]
	v_lshlrev_b32_e32 v75, 16, v35
	v_lshlrev_b32_e32 v74, 16, v34
	v_pk_mul_f32 v[74:75], v[76:77], v[74:75]
	v_and_b32_e32 v35, 0xffff0000, v35
	v_and_b32_e32 v34, 0xffff0000, v34
	v_mov_b32_e32 v76, v39
	v_mov_b32_e32 v77, v41
	v_pk_mul_f32 v[34:35], v[76:77], v[34:35]
	v_lshlrev_b32_e32 v77, 16, v37
	v_lshlrev_b32_e32 v76, 16, v36
	v_pk_mul_f32 v[76:77], v[84:85], v[76:77]
	v_and_b32_e32 v37, 0xffff0000, v37
	v_and_b32_e32 v36, 0xffff0000, v36
	v_mov_b32_e32 v84, v79
	v_mov_b32_e32 v85, v81
	v_pk_mul_f32 v[36:37], v[84:85], v[36:37]
	v_bfe_u32 v85, v35, 16, 1
	v_bfe_u32 v1, v37, 16, 1
	v_bfe_u32 v84, v36, 16, 1
	v_bfe_u32 v86, v34, 16, 1
	v_add3_u32 v34, v34, v86, s81
	v_add3_u32 v35, v35, v85, s81
	v_add3_u32 v36, v36, v84, s81
	v_add3_u32 v1, v37, v1, s81
	v_bfe_u32 v37, v74, 16, 1
	v_bfe_u32 v84, v75, 16, 1
	v_bfe_u32 v85, v76, 16, 1
	v_bfe_u32 v86, v77, 16, 1
	v_add3_u32 v77, v77, v86, s81
	v_add3_u32 v76, v76, v85, s81
	v_add3_u32 v75, v75, v84, s81
	v_add3_u32 v37, v74, v37, s81
	v_lshrrev_b32_e32 v37, 16, v37
	v_lshrrev_b32_e32 v74, 16, v75
	v_lshrrev_b32_e32 v75, 16, v76
	v_lshrrev_b32_e32 v76, 16, v77
	v_and_or_b32 v77, v1, s80, v76
	v_and_or_b32 v76, v36, s80, v75
	v_and_or_b32 v75, v35, s80, v74
	v_and_or_b32 v74, v34, s80, v37
	v_bfe_u32 v34, v79, 16, 1
	v_bfe_u32 v35, v41, 16, 1
	v_bfe_u32 v36, v39, 16, 1
	v_add3_u32 v36, v39, v36, s81
	v_add3_u32 v35, v41, v35, s81
	v_add3_u32 v34, v79, v34, s81
	v_bfe_u32 v39, v40, 16, 1
	v_bfe_u32 v41, v78, 16, 1
	v_bfe_u32 v79, v80, 16, 1
	v_bfe_u32 v1, v81, 16, 1
	v_bfe_u32 v37, v38, 16, 1
	v_add3_u32 v79, v80, v79, s81
	v_add3_u32 v41, v78, v41, s81
	v_add3_u32 v39, v40, v39, s81
	v_add3_u32 v1, v81, v1, s81
	v_add3_u32 v37, v38, v37, s81
	v_lshrrev_b32_e32 v38, 16, v39
	v_lshrrev_b32_e32 v39, 16, v41
	v_lshrrev_b32_e32 v40, 16, v79
	v_and_or_b32 v81, v1, s80, v40
	v_and_or_b32 v80, v34, s80, v39
	v_and_or_b32 v79, v35, s80, v38
	ds_read_b64_tr_b16 v[38:39], v220 offset:9728
	ds_read_b64_tr_b16 v[40:41], v220 offset:10816
	v_lshrrev_b32_e32 v37, 16, v37
	v_and_or_b32 v78, v36, s80, v37
	s_waitcnt lgkmcnt(0)
	v_mfma_f32_16x16x32_bf16 v[34:37], v[74:77], v[38:41], v[70:73]
	s_cbranch_vccnz .LBB0_651
	v_mfma_f32_16x16x32_bf16 v[2:5], v[78:81], v[38:41], v[2:5]

; #define LAS __attribute__((address_space(3)))
; __device__ __forceinline__ unsigned pk2(float lo, float hi) { return f2bf(lo) | (f2bf(hi) << 16); }
; __device__ __forceinline__ float bf_lo(unsigned w) { return __uint_as_float(w << 16); }
; __device__ __forceinline__ float bf_hi(unsigned w) { return __uint_as_float(w & 0xffff0000u); }
; __device__ __forceinline__ f32x4 mfma16(bf16x8 a, bf16x8 b, f32x4 c) { return __builtin_amdgcn_mfma_f32_16x16x32_bf16(a, b, c, 0, 0, 0); }
; template <int MASK> __device__ __forceinline__ void phase3(const Args& a, LAS unsigned char* lds, int tid, int wave, int lane, int vcu, int G) {
;     ...
;             for (int ks = 0; ks < 4; ++ks) {
;                 const u32x4 aw = __builtin_bit_cast(u32x4, ldfrag(vt + 32 * ks));
;                 const f32x4 w0 = *(const LAS f32x4*)(wl + 32 * ks + 8 * g), w1 = *(const LAS f32x4*)(wl + 32 * ks + 8 * g + 4);
;                 u32x4 as, a1;
;                 as.x = pk2(bf_lo(aw.x) * w0[0], bf_hi(aw.x) * w0[1]); as.y = pk2(bf_lo(aw.y) * w0[2], bf_hi(aw.y) * w0[3]);
;                 as.z = pk2(bf_lo(aw.z) * w1[0], bf_hi(aw.z) * w1[1]); as.w = pk2(bf_lo(aw.w) * w1[2], bf_hi(aw.w) * w1[3]);
;                 a1.x = pk2(w0[0], w0[1]); a1.y = pk2(w0[2], w0[3]); a1.z = pk2(w1[0], w1[1]); a1.w = pk2(w1[2], w1[3]);
;                 const bf16x8 af = __builtin_bit_cast(bf16x8, as), af1 = __builtin_bit_cast(bf16x8, a1);
; #pragma unroll
;                 for (int n = 0; n < 8; ++n) {
;                     typedef short v4i16_t __attribute__((ext_vector_type(4)));
;                     const v4i16_t lo = __builtin_amdgcn_ds_read_tr16_b64_v4i16((LAS v4i16_t*)(LK + (32 * ks + 8 * g + q4) * 272 + 32 * n + 8 * p4));
;                     const v4i16_t hi = __builtin_amdgcn_ds_read_tr16_b64_v4i16((LAS v4i16_t*)(LK + (32 * ks + 8 * g + 4 + q4) * 272 + 32 * n + 8 * p4));
;                     const bf16x8 bfr = {lo[0], lo[1], lo[2], lo[3], hi[0], hi[1], hi[2], hi[3]};
;                     acc[n] = mfma16(af, bfr, acc[n]); if (wave == 0) accn[n] = mfma16(af1, bfr, accn[n]); }
.LBB0_665:
	s_nop 0
	s_nop 0
	ds_read_b128 v[70:73], v212 offset:256
	ds_read_b128 v[74:77], v212 offset:272
	s_and_b64 vcc, exec, s[48:49]
	s_waitcnt lgkmcnt(1)
	v_mov_b32_e32 v80, v70
	v_mov_b32_e32 v81, v72
	s_waitcnt lgkmcnt(0)
	v_mov_b32_e32 v84, v74
	v_mov_b32_e32 v85, v76
	s_waitcnt vmcnt(1)
	v_mov_b64_e32 v[66:67], v[174:175]
	v_mov_b64_e32 v[68:69], v[176:177]
	v_lshlrev_b32_e32 v79, 16, v67
	v_lshlrev_b32_e32 v78, 16, v66
	v_pk_mul_f32 v[78:79], v[80:81], v[78:79]
	v_and_b32_e32 v67, 0xffff0000, v67
	v_and_b32_e32 v66, 0xffff0000, v66
	v_mov_b32_e32 v80, v71
	v_mov_b32_e32 v81, v73
	v_pk_mul_f32 v[66:67], v[80:81], v[66:67]
	v_lshlrev_b32_e32 v81, 16, v69
	v_lshlrev_b32_e32 v80, 16, v68
	v_pk_mul_f32 v[80:81], v[84:85], v[80:81]
	v_and_b32_e32 v69, 0xffff0000, v69
	v_and_b32_e32 v68, 0xffff0000, v68
	v_mov_b32_e32 v84, v75
	v_mov_b32_e32 v85, v77
	v_pk_mul_f32 v[68:69], v[84:85], v[68:69]
	v_bfe_u32 v86, v66, 16, 1
	v_bfe_u32 v1, v69, 16, 1
	v_bfe_u32 v84, v68, 16, 1
	v_bfe_u32 v85, v67, 16, 1
	v_add3_u32 v66, v66, v86, s81
	v_add3_u32 v1, v69, v1, s81
	v_bfe_u32 v69, v78, 16, 1
	v_bfe_u32 v86, v81, 16, 1
	v_add3_u32 v67, v67, v85, s81
	v_add3_u32 v68, v68, v84, s81
	v_bfe_u32 v84, v79, 16, 1
	v_bfe_u32 v85, v80, 16, 1
	v_add3_u32 v81, v81, v86, s81
	v_add3_u32 v69, v78, v69, s81
	v_add3_u32 v80, v80, v85, s81
	v_add3_u32 v79, v79, v84, s81
	v_lshrrev_b32_e32 v78, 16, v69
	v_lshrrev_b32_e32 v69, 16, v81
	v_lshrrev_b32_e32 v79, 16, v79
	v_lshrrev_b32_e32 v80, 16, v80
	v_and_or_b32 v69, v1, s80, v69
	v_and_or_b32 v66, v66, s80, v78
	v_bfe_u32 v1, v77, 16, 1
	v_bfe_u32 v78, v75, 16, 1
	v_and_or_b32 v68, v68, s80, v80
	v_and_or_b32 v67, v67, s80, v79
	v_bfe_u32 v79, v73, 16, 1
	v_bfe_u32 v80, v71, 16, 1
	v_add3_u32 v75, v75, v78, s81
	v_add3_u32 v1, v77, v1, s81
	v_bfe_u32 v77, v72, 16, 1
	v_bfe_u32 v78, v74, 16, 1
	v_add3_u32 v80, v71, v80, s81
	v_add3_u32 v71, v73, v79, s81
	v_bfe_u32 v79, v76, 16, 1
	v_add3_u32 v74, v74, v78, s81
	v_add3_u32 v72, v72, v77, s81
	v_bfe_u32 v73, v70, 16, 1
	v_add3_u32 v76, v76, v79, s81
	v_lshrrev_b32_e32 v77, 16, v72
	v_lshrrev_b32_e32 v72, 16, v74
	v_add3_u32 v70, v70, v73, s81
	v_lshrrev_b32_e32 v73, 16, v76
	v_and_or_b32 v72, v75, s80, v72
	v_and_or_b32 v71, v71, s80, v77
	ds_read_b64_tr_b16 v[74:75], v220 offset:18432
	ds_read_b64_tr_b16 v[76:77], v220 offset:19520
	s_waitcnt lgkmcnt(0)
	v_mfma_f32_16x16x32_bf16 v[34:37], v[66:69], v[74:77], v[34:37]
	v_lshrrev_b32_e32 v70, 16, v70
	v_and_or_b32 v73, v1, s80, v73
	v_and_or_b32 v70, v80, s80, v70
	s_cbranch_vccnz .LBB0_667
	s_nop 0
	v_mfma_f32_16x16x32_bf16 v[2:5], v[70:73], v[74:77], v[2:5]

; #define LAS __attribute__((address_space(3)))
; __device__ __forceinline__ unsigned pk2(float lo, float hi) { return f2bf(lo) | (f2bf(hi) << 16); }
; __device__ __forceinline__ float bf_lo(unsigned w) { return __uint_as_float(w << 16); }
; __device__ __forceinline__ float bf_hi(unsigned w) { return __uint_as_float(w & 0xffff0000u); }
; __device__ __forceinline__ f32x4 mfma16(bf16x8 a, bf16x8 b, f32x4 c) { return __builtin_amdgcn_mfma_f32_16x16x32_bf16(a, b, c, 0, 0, 0); }
; template <int MASK> __device__ __forceinline__ void phase3(const Args& a, LAS unsigned char* lds, int tid, int wave, int lane, int vcu, int G) {
;     ...
;             for (int ks = 0; ks < 4; ++ks) {
;                 const u32x4 aw = __builtin_bit_cast(u32x4, ldfrag(vt + 32 * ks));
;                 const f32x4 w0 = *(const LAS f32x4*)(wl + 32 * ks + 8 * g), w1 = *(const LAS f32x4*)(wl + 32 * ks + 8 * g + 4);
;                 u32x4 as, a1;
;                 as.x = pk2(bf_lo(aw.x) * w0[0], bf_hi(aw.x) * w0[1]); as.y = pk2(bf_lo(aw.y) * w0[2], bf_hi(aw.y) * w0[3]);
;                 as.z = pk2(bf_lo(aw.z) * w1[0], bf_hi(aw.z) * w1[1]); as.w = pk2(bf_lo(aw.w) * w1[2], bf_hi(aw.w) * w1[3]);
;                 a1.x = pk2(w0[0], w0[1]); a1.y = pk2(w0[2], w0[3]); a1.z = pk2(w1[0], w1[1]); a1.w = pk2(w1[2], w1[3]);
;                 const bf16x8 af = __builtin_bit_cast(bf16x8, as), af1 = __builtin_bit_cast(bf16x8, a1);
; #pragma unroll
;                 for (int n = 0; n < 8; ++n) {
;                     typedef short v4i16_t __attribute__((ext_vector_type(4)));
;                     const v4i16_t lo = __builtin_amdgcn_ds_read_tr16_b64_v4i16((LAS v4i16_t*)(LK + (32 * ks + 8 * g + q4) * 272 + 32 * n + 8 * p4));
;                     const v4i16_t hi = __builtin_amdgcn_ds_read_tr16_b64_v4i16((LAS v4i16_t*)(LK + (32 * ks + 8 * g + 4 + q4) * 272 + 32 * n + 8 * p4));
;                     const bf16x8 bfr = {lo[0], lo[1], lo[2], lo[3], hi[0], hi[1], hi[2], hi[3]};
;                     acc[n] = mfma16(af, bfr, acc[n]); if (wave == 0) accn[n] = mfma16(af1, bfr, accn[n]); }
.LBB0_681:
	s_nop 0
	ds_read_b128 v[70:73], v212 offset:384
	ds_read_b128 v[74:77], v212 offset:400
	s_and_b64 vcc, exec, s[48:49]
	s_waitcnt lgkmcnt(1)
	v_mov_b32_e32 v80, v70
	v_mov_b32_e32 v81, v72
	s_waitcnt lgkmcnt(0)
	v_mov_b32_e32 v82, v74
	v_mov_b32_e32 v83, v76
	s_waitcnt vmcnt(0)
	v_mov_b64_e32 v[66:67], v[178:179]
	v_mov_b64_e32 v[68:69], v[180:181]
	v_lshlrev_b32_e32 v79, 16, v67
	v_lshlrev_b32_e32 v78, 16, v66
	v_pk_mul_f32 v[78:79], v[80:81], v[78:79]
	v_and_b32_e32 v67, 0xffff0000, v67
	v_and_b32_e32 v66, 0xffff0000, v66
	v_mov_b32_e32 v80, v71
	v_mov_b32_e32 v81, v73
	v_pk_mul_f32 v[66:67], v[80:81], v[66:67]
	v_lshlrev_b32_e32 v81, 16, v69
	v_lshlrev_b32_e32 v80, 16, v68
	v_pk_mul_f32 v[80:81], v[82:83], v[80:81]
	v_and_b32_e32 v69, 0xffff0000, v69
	v_and_b32_e32 v68, 0xffff0000, v68
	v_mov_b32_e32 v82, v75
	v_mov_b32_e32 v83, v77
	v_pk_mul_f32 v[68:69], v[82:83], v[68:69]
	v_bfe_u32 v84, v66, 16, 1
	v_bfe_u32 v1, v69, 16, 1
	v_bfe_u32 v82, v68, 16, 1
	v_bfe_u32 v83, v67, 16, 1
	v_add3_u32 v66, v66, v84, s81
	v_add3_u32 v1, v69, v1, s81
	v_bfe_u32 v69, v78, 16, 1
	v_bfe_u32 v84, v81, 16, 1
	v_add3_u32 v67, v67, v83, s81
	v_add3_u32 v68, v68, v82, s81
	v_bfe_u32 v82, v79, 16, 1
	v_bfe_u32 v83, v80, 16, 1
	v_add3_u32 v81, v81, v84, s81
	v_add3_u32 v69, v78, v69, s81
	v_add3_u32 v80, v80, v83, s81
	v_add3_u32 v79, v79, v82, s81
	v_lshrrev_b32_e32 v78, 16, v69
	v_lshrrev_b32_e32 v69, 16, v81
	v_lshrrev_b32_e32 v79, 16, v79
	v_lshrrev_b32_e32 v80, 16, v80
	v_and_or_b32 v69, v1, s80, v69
	v_and_or_b32 v66, v66, s80, v78
	v_bfe_u32 v1, v77, 16, 1
	v_bfe_u32 v78, v75, 16, 1
	v_and_or_b32 v68, v68, s80, v80
	v_and_or_b32 v67, v67, s80, v79
	v_bfe_u32 v79, v73, 16, 1
	v_bfe_u32 v80, v71, 16, 1
	v_add3_u32 v75, v75, v78, s81
	v_add3_u32 v1, v77, v1, s81
	v_bfe_u32 v77, v72, 16, 1
	v_bfe_u32 v78, v74, 16, 1
	v_add3_u32 v80, v71, v80, s81
	v_add3_u32 v71, v73, v79, s81
	v_bfe_u32 v79, v76, 16, 1
	v_add3_u32 v74, v74, v78, s81
	v_add3_u32 v72, v72, v77, s81
	v_bfe_u32 v73, v70, 16, 1
	v_add3_u32 v76, v76, v79, s81
	v_lshrrev_b32_e32 v77, 16, v72
	v_lshrrev_b32_e32 v72, 16, v74
	v_add3_u32 v70, v70, v73, s81
	v_lshrrev_b32_e32 v73, 16, v76
	v_and_or_b32 v72, v75, s80, v72
	v_and_or_b32 v71, v71, s80, v77
	ds_read_b64_tr_b16 v[74:75], v220 offset:27136
	ds_read_b64_tr_b16 v[76:77], v220 offset:28224
	s_waitcnt lgkmcnt(0)
	v_mfma_f32_16x16x32_bf16 v[34:37], v[66:69], v[74:77], v[34:37]
	v_lshrrev_b32_e32 v70, 16, v70
	v_and_or_b32 v73, v1, s80, v73
	v_and_or_b32 v70, v80, s80, v70
	s_cbranch_vccnz .LBB0_683
	s_nop 0
	v_mfma_f32_16x16x32_bf16 v[2:5], v[70:73], v[74:77], v[2:5]
